# every workgroup's acquire is again agent-scope (buffer_inv sc1), but issued right after it arrives at the barrier so it overlaps the wait; XCD leaders invalidate after their L2 writeback (full) or aft
# speedup vs baseline: 1.0028x; 1.0028x over previous
.LBB0_91:
	s_or_b64 exec, exec, s[12:13]
	v_cvt_f32_u32_e32 v4, v2
	s_waitcnt vmcnt(0)
	v_readfirstlane_b32 s0, v3
	v_sub_u32_e32 v3, 0, v2
	v_rcp_iflag_f32_e32 v4, v4
	v_add_u32_e32 v5, s0, v0
	v_mul_f32_e32 v4, 0x4f7ffffe, v4
	v_cvt_u32_f32_e32 v4, v4
	v_mul_lo_u32 v0, v3, v4
	v_mul_hi_u32 v0, v4, v0
	v_add_u32_e32 v0, v4, v0
	v_mul_hi_u32 v0, v5, v0
	v_mul_lo_u32 v3, v0, v2
	v_sub_u32_e32 v3, v5, v3
	v_add_u32_e32 v4, 1, v0
	v_cmp_ge_u32_e32 vcc, v3, v2
	s_nop 1
	v_cndmask_b32_e32 v0, v0, v4, vcc
	v_sub_u32_e32 v4, v3, v2
	v_cndmask_b32_e32 v3, v3, v4, vcc
	v_add_u32_e32 v4, 1, v0
	v_cmp_ge_u32_e32 vcc, v3, v2
	v_add_u32_e32 v3, 1, v5
	s_nop 0
	v_cndmask_b32_e32 v0, v0, v4, vcc
	v_mul_lo_u32 v4, v2, v0
	v_add_u32_e32 v2, v4, v2
	v_cmp_ne_u32_e32 vcc, v3, v2
	s_and_saveexec_b64 s[0:1], vcc
	s_xor_b64 s[10:11], exec, s[0:1]
	s_cbranch_execz .LBB0_114
	buffer_inv sc1
	s_add_u32 s12, s8, 0x2400
	s_addc_u32 s13, s9, 0
	s_mov_b32 s0, 0x1000000
	s_mov_b64 s[14:15], 0
	v_mov_b32_e32 v1, 0
	s_branch .LBB0_102

.LBB0_113:
	s_or_b64 exec, exec, s[14:15]
	s_waitcnt lgkmcnt(0)
	s_waitcnt vmcnt(0)

.LBB0_180:
	s_or_b64 exec, exec, s[12:13]
	v_cvt_f32_u32_e32 v5, v3
	s_waitcnt vmcnt(0)
	v_readfirstlane_b32 s2, v4
	v_sub_u32_e32 v4, 0, v3
	v_rcp_iflag_f32_e32 v5, v5
	v_add_u32_e32 v6, s2, v0
	v_mul_f32_e32 v5, 0x4f7ffffe, v5
	v_cvt_u32_f32_e32 v5, v5
	v_mul_lo_u32 v0, v4, v5
	v_mul_hi_u32 v0, v5, v0
	v_add_u32_e32 v0, v5, v0
	v_mul_hi_u32 v0, v6, v0
	v_mul_lo_u32 v4, v0, v3
	v_sub_u32_e32 v4, v6, v4
	v_add_u32_e32 v5, 1, v0
	v_cmp_ge_u32_e32 vcc, v4, v3
	s_nop 1
	v_cndmask_b32_e32 v0, v0, v5, vcc
	v_sub_u32_e32 v5, v4, v3
	v_cndmask_b32_e32 v4, v4, v5, vcc
	v_add_u32_e32 v5, 1, v0
	v_cmp_ge_u32_e32 vcc, v4, v3
	v_add_u32_e32 v4, 1, v6
	s_nop 0
	v_cndmask_b32_e32 v0, v0, v5, vcc
	v_mul_lo_u32 v5, v3, v0
	v_add_u32_e32 v3, v5, v3
	v_cmp_ne_u32_e32 vcc, v4, v3
	s_and_saveexec_b64 s[2:3], vcc
	s_xor_b64 s[10:11], exec, s[2:3]
	s_cbranch_execz .LBB0_203
	buffer_inv sc1
	s_add_u32 s12, s8, 0x2400
	s_addc_u32 s13, s9, 0
	s_mov_b32 s2, 0x1000000
	s_mov_b64 s[14:15], 0
	s_branch .LBB0_191

.Lglu_nowb:
	s_waitcnt lgkmcnt(0)
	s_waitcnt vmcnt(0)
	buffer_inv sc1
	v_mbcnt_lo_u32_b32 v0, s10, 0
	v_mbcnt_hi_u32_b32 v0, s11, v0
	v_cmp_eq_u32_e32 vcc, 0, v0
	s_and_saveexec_b64 s[12:13], vcc
	s_cbranch_execz .LBB0_562
	s_bcnt1_i32_b64 s2, s[10:11]
	v_mov_b32_e32 v3, s2
	global_atomic_add v3, v254, v3, s[6:7] offset:1024 sc0

.LBB0_726:
	s_andn2_saveexec_b64 s[2:3], s[10:11]
	s_cbranch_execz .LBB0_759
	s_mov_b64 s[10:11], exec
	v_readlane_b32 s2, v255, 40
	s_nop 0
	s_cmp_lg_u32 s2, 0
	s_cbranch_scc0 .Lfullb_756
	v_mov_b32_e32 v0, 1
	global_atomic_add v231, v0, s[8:9] offset:1024
	buffer_inv sc1
	s_branch .LBB0_758
.Lfullb_756:
	buffer_wbl2 sc1
	s_waitcnt vmcnt(0)
	buffer_inv sc1
	s_waitcnt lgkmcnt(0)
	s_waitcnt vmcnt(0)
	v_mbcnt_lo_u32_b32 v0, s10, 0
	v_mbcnt_hi_u32_b32 v0, s11, v0
	v_cmp_eq_u32_e32 vcc, 0, v0
	s_and_saveexec_b64 s[12:13], vcc
	s_cbranch_execz .LBB0_729
	s_bcnt1_i32_b64 s2, s[10:11]
	v_mov_b32_e32 v3, s2
	global_atomic_add v3, v254, v3, s[6:7] offset:1024 sc0

.LBB0_1116:
	s_or_b64 exec, exec, s[14:15]
	v_cvt_f32_u32_e32 v5, v3
	s_waitcnt vmcnt(0)
	v_readfirstlane_b32 s2, v4
	v_sub_u32_e32 v4, 0, v3
	v_rcp_iflag_f32_e32 v5, v5
	v_add_u32_e32 v6, s2, v0
	v_mul_f32_e32 v5, 0x4f7ffffe, v5
	v_cvt_u32_f32_e32 v5, v5
	v_mul_lo_u32 v0, v4, v5
	v_mul_hi_u32 v0, v5, v0
	v_add_u32_e32 v0, v5, v0
	v_mul_hi_u32 v0, v6, v0
	v_mul_lo_u32 v4, v0, v3
	v_sub_u32_e32 v4, v6, v4
	v_add_u32_e32 v5, 1, v0
	v_cmp_ge_u32_e32 vcc, v4, v3
	s_nop 1
	v_cndmask_b32_e32 v0, v0, v5, vcc
	v_sub_u32_e32 v5, v4, v3
	v_cndmask_b32_e32 v4, v4, v5, vcc
	v_add_u32_e32 v5, 1, v0
	v_cmp_ge_u32_e32 vcc, v4, v3
	v_add_u32_e32 v4, 1, v6
	s_nop 0
	v_cndmask_b32_e32 v0, v0, v5, vcc
	v_mul_lo_u32 v5, v3, v0
	v_add_u32_e32 v3, v5, v3
	v_cmp_ne_u32_e32 vcc, v4, v3
	s_and_saveexec_b64 s[2:3], vcc
	s_xor_b64 s[12:13], exec, s[2:3]
	s_cbranch_execz .LBB0_1139
	buffer_inv sc1
	s_add_u32 s14, s8, 0x2400
	s_addc_u32 s15, s9, 0
	s_mov_b32 s2, 0x1000000
	s_mov_b64 s[16:17], 0
	s_branch .LBB0_1127

.LBB0_1138:
	s_or_b64 exec, exec, s[16:17]
	s_waitcnt lgkmcnt(0)
	s_waitcnt vmcnt(0)
.LBB0_1139:
	s_andn2_saveexec_b64 s[2:3], s[12:13]
	s_cbranch_execz .LBB0_1172
	s_mov_b64 s[12:13], exec
	v_readlane_b32 s2, v255, 40
	s_nop 0
	s_cmp_lg_u32 s2, 0
	s_cbranch_scc0 .Lfullb_1169
	v_mov_b32_e32 v0, 1
	global_atomic_add v231, v0, s[8:9] offset:1024
	buffer_inv sc1
	s_branch .LBB0_1171
.Lfullb_1169:
	buffer_wbl2 sc1
	s_waitcnt vmcnt(0)
	buffer_inv sc1
	s_waitcnt lgkmcnt(0)
	s_waitcnt vmcnt(0)
	v_mbcnt_lo_u32_b32 v0, s12, 0
	v_mbcnt_hi_u32_b32 v0, s13, v0
	v_cmp_eq_u32_e32 vcc, 0, v0
	s_and_saveexec_b64 s[14:15], vcc
	s_cbranch_execz .LBB0_1142
	s_bcnt1_i32_b64 s2, s[12:13]
	v_mov_b32_e32 v3, s2
	global_atomic_add v3, v254, v3, s[6:7] offset:1024 sc0

.LBB0_1169:
	s_or_b64 exec, exec, s[12:13]
	s_mov_b64 s[6:7], exec
	v_mbcnt_lo_u32_b32 v0, s6, 0
	v_mbcnt_hi_u32_b32 v0, s7, v0
	v_cmp_eq_u32_e32 vcc, 0, v0
	s_waitcnt vmcnt(0)
	s_and_saveexec_b64 s[12:13], vcc
	s_cbranch_execz .LBB0_1171
	s_bcnt1_i32_b64 s2, s[6:7]
	v_mov_b32_e32 v0, s2
	global_atomic_add v231, v0, s[8:9] offset:1024

.LBB0_1344:
	s_mov_b64 s[12:13], exec
	v_readlane_b32 s2, v255, 40
	s_and_b64 vcc, exec, s[10:11]
	s_cselect_b32 s3, 1, 0
	s_and_b32 s2, s2, s3
	s_cmp_lg_u32 s2, 0
	s_cbranch_scc0 .Lfullb_1373
	v_mov_b32_e32 v0, 1
	global_atomic_add v231, v0, s[8:9] offset:1024
	buffer_inv sc1
	s_branch .Lb2_tail

.Lb2_tail:
	s_getpc_b64 s[98:99]
